# v17 plus scalar overhead stripped from the MLA loop: unmasked duplicate rotary-key LDS write (no saveexec/branch), loop-invariant 64-bit constants hoisted, SCC exit test
# speedup vs baseline: 1.0062x; 1.0017x over previous
; #define SLOAD(i, k0) do { st_[i].vs = *reinterpret_cast<const bf16x8*>(&Vh[(size_t)((k0) + sr) * LDK + sc]); \
;     st_[i].ks = *reinterpret_cast<const bf16x8*>(&Kh[(size_t)((k0) + sr) * LDK + sc]); \
;     if (DQ == 96) st_[i].kr = *reinterpret_cast<const bf16x8*>(&Kr[(size_t)((k0) + sr2) * 32 + sc2]); } while (0)
; #define SWRITE(b, i) do { *(bf16x8*)(V_lds + (b) * SHM_V + vst0) = st_[i].vs; *(bf16x8*)(K_lds + (b) * SHM_K + kst0) = st_[i].ks; \
;     if (DQ == 96) { if (tid < 256) *(bf16x8*)(K_lds + (b) * SHM_K + kst2) = st_[i].kr; } } while (0)
; #define SWAIT() do { if (DQ == 96) asm volatile("s_waitcnt vmcnt(3)" ::: "memory"); else asm volatile("s_waitcnt vmcnt(2)" ::: "memory"); } while (0)
; #define SLOAD(i, k0) do { st_[i].vs = *reinterpret_cast<const bf16x8*>(&Vh[(size_t)((k0) + sr) * LDK + sc]); \
;     st_[i].ks = *reinterpret_cast<const bf16x8*>(&Kh[(size_t)((k0) + sr) * LDK + sc]); \
;     if (DQ == 96) st_[i].kr = *reinterpret_cast<const bf16x8*>(&Kr[(size_t)((k0) + sr2) * 32 + sc2]); } while (0)
; #define SWRITE(b, i) do { *(bf16x8*)(V_lds + (b) * SHM_V + vst0) = st_[i].vs; *(bf16x8*)(K_lds + (b) * SHM_K + kst0) = st_[i].ks; \
;     if (DQ == 96) { if (tid < 256) *(bf16x8*)(K_lds + (b) * SHM_K + kst2) = st_[i].kr; } } while (0)
; __device__ __forceinline__ float row_max32(const f32x16& p0, const f32x16& p1) {
;     float pmax = p0[0];
; #pragma unroll
;     for (int r = 1; r < 16; ++r) pmax = fmaxf(pmax, p0[r]);
; #pragma unroll
;     for (int r = 0; r < 16; ++r) pmax = fmaxf(pmax, p1[r]);
;     auto rr = __builtin_amdgcn_permlane32_swap(__float_as_uint(pmax), __float_as_uint(pmax), false, false);
;     return fmaxf(__uint_as_float(rr[0]), __uint_as_float(rr[1]));
; }
; template <int DQ, bool WIN, int LDQ, int LDK> ...
;     ...
;     SLOAD(SE, KBASE(0)); SLOAD(SO, KBASE(1));
;     SWAIT(); SWRITE(0, SE); __syncthreads();
;     qkt<DQ>(pA0, pA1, K_lds, qr, zero16, r32, hi);
;     if (WIN) win_mask(pA0, pA1, qrow - KBASE(0), hi);
;     { const float pm = row_max32(pA0, pA1); m_ref = (pm > -1e37f) ? pm : 0.f;
; #pragma unroll
;       for (int r = 0; r < 16; ++r) { minit[r] = -m_ref; pA0[r] -= m_ref; pA1[r] -= m_ref; } }
;     exp16(pA0);
;     if (2 < NT) SLOAD(SE, KBASE(2));
;     SWAIT(); SWRITE(1, SO); __syncthreads();
.LBB0_1088:
	s_or_b64 exec, exec, s[16:17]
	v_and_b32_e32 v188, 31, v80
	s_movk_i32 s16, 0xd0
	v_mad_u32_u24 v0, v188, s16, 0
	v_add_u32_e32 v191, v0, v112
	s_waitcnt lgkmcnt(0)
	s_barrier
	ds_read_b128 v[0:3], v191 offset:16384
	ds_read_b128 v[52:55], v191 offset:16416
	s_waitcnt lgkmcnt(1)
	v_mfma_f32_32x32x16_bf16 v[16:31], v[0:3], v[134:137], 0
	ds_read_b128 v[0:3], v191 offset:23040
	ds_read_b128 v[56:59], v191 offset:23072
	v_lshl_or_b32 v50, v50, 1, v44
	v_mov_b32_e32 v51, v45
	v_lshl_add_u64 v[50:51], s[6:7], 0, v[50:51]
	s_mov_b64 s[16:17], 0x80000
	s_waitcnt lgkmcnt(1)
	v_mfma_f32_32x32x16_bf16 v[0:15], v[0:3], v[134:137], 0
	v_mfma_f32_32x32x16_bf16 v[16:31], v[52:55], v[130:133], v[16:31]
	s_waitcnt lgkmcnt(0)
	v_mfma_f32_32x32x16_bf16 v[0:15], v[56:59], v[130:133], v[0:15]
	ds_read_b128 v[52:55], v191 offset:16448
	ds_read_b128 v[56:59], v191 offset:16480
	s_waitcnt lgkmcnt(1)
	v_mfma_f32_32x32x16_bf16 v[16:31], v[52:55], v[126:129], v[16:31]
	ds_read_b128 v[52:55], v191 offset:23104
	ds_read_b128 v[60:63], v191 offset:23136
	s_waitcnt lgkmcnt(2)
	v_mfma_f32_32x32x16_bf16 v[16:31], v[56:59], v[122:125], v[16:31]
	v_lshl_add_u64 v[56:57], v[50:51], 0, s[16:17]
	v_add_co_u32_e32 v50, vcc, 0x80000, v50
	s_mov_b32 s16, 0xfcf0bdc2
	s_nop 0
	v_addc_co_u32_e32 v51, vcc, 0, v51, vcc
	v_add_co_u32_e32 v46, vcc, 0x2000, v46
	s_waitcnt lgkmcnt(1)
	v_mfma_f32_32x32x16_bf16 v[0:15], v[52:55], v[126:129], v[0:15]
	v_addc_co_u32_e32 v47, vcc, 0, v47, vcc
	ds_read_b128 v[52:55], v191 offset:16512
	ds_read_b128 v[64:67], v191 offset:16544
	global_load_dwordx4 v[138:141], v[56:57], off offset:128
	global_load_dwordx4 v[142:145], v[50:51], off
	global_load_dwordx4 v[146:149], v[46:47], off
	s_waitcnt lgkmcnt(1)
	v_mfma_f32_32x32x16_bf16 v[16:31], v[52:55], v[118:121], v[16:31]
	ds_read_b128 v[50:53], v191 offset:23168
	ds_read_b128 v[54:57], v191 offset:23200
	s_waitcnt vmcnt(3)
	ds_write_b128 v192, v[36:39] offset:8192
	ds_write_b128 v193, v[40:43] offset:29696
	v_add_u32_e32 v36, v48, v49
	v_mfma_f32_32x32x16_bf16 v[0:15], v[60:63], v[122:125], v[0:15]
	s_waitcnt lgkmcnt(4)
	v_mfma_f32_32x32x16_bf16 v[16:31], v[64:67], v[114:117], v[16:31]
	s_waitcnt lgkmcnt(3)
	v_mfma_f32_32x32x16_bf16 v[0:15], v[50:53], v[118:121], v[0:15]
	s_nop 9
	v_max_f32_e32 v46, v17, v17
	v_max_f32_e32 v47, v16, v16
	v_max_f32_e32 v46, v47, v46
	v_max3_f32 v46, v46, v18, v19
	v_max3_f32 v46, v46, v20, v21
	v_max3_f32 v46, v46, v22, v23
	v_max3_f32 v46, v46, v24, v25
	s_waitcnt lgkmcnt(2)
	v_mfma_f32_32x32x16_bf16 v[0:15], v[54:57], v[114:117], v[0:15]
	v_max3_f32 v46, v46, v26, v27
	v_max3_f32 v46, v46, v28, v29
	v_max3_f32 v46, v46, v30, v31
	s_nop 8
	v_max3_f32 v46, v46, v0, v1
	v_max3_f32 v46, v46, v2, v3
	v_max3_f32 v46, v46, v4, v5
	v_max3_f32 v46, v46, v6, v7
	v_max3_f32 v46, v46, v8, v9
	v_max3_f32 v46, v46, v10, v11
	v_max3_f32 v46, v46, v12, v13
	v_max3_f32 v46, v46, v14, v15
	v_mov_b32_e32 v47, v46
	s_nop 1
	v_permlane32_swap_b32_e32 v46, v47
	v_max_f32_e32 v47, v47, v47
	v_max_f32_e32 v46, v46, v46
	v_max_f32_e32 v46, v46, v47
	v_cmp_lt_f32_e32 vcc, s16, v46
	s_and_saveexec_b64 s[16:17], s[4:5]
	s_xor_b64 s[4:5], exec, s[16:17]
	v_add_u32_e32 v36, v48, v49
	s_andn2_saveexec_b64 s[4:5], s[4:5]
	v_add_u32_e32 v37, 0, v36
	ds_write_b128 v37, v[32:35] offset:29824
	s_or_b64 exec, exec, s[4:5]
	v_and_b32_e32 v189, 63, v80
	v_cndmask_b32_e32 v32, 0, v46, vcc
	v_sub_f32_e32 v65, v1, v32
	v_lshlrev_b32_e32 v1, 4, v189
	s_lshr_b32 s4, s20, 5
	s_and_b32 s16, s18, 0xffffffe0
	v_sub_f32_e32 v66, v2, v32
	v_sub_f32_e32 v64, v0, v32
	v_lshlrev_b32_e32 v0, 3, v189
	v_and_b32_e32 v1, 0xc0, v1
	v_lshlrev_b32_e32 v2, 1, v189
	v_and_or_b32 v1, v0, 24, v1
	v_and_b32_e32 v2, 32, v2
	v_and_b32_e32 v0, 0x100, v0
	s_cmp_lg_u32 0, -1
	v_or3_b32 v0, v1, v2, v0
	s_cselect_b32 s5, 0, 0
	s_and_b32 s4, s4, 15
	v_add_u32_e32 v194, s5, v0
	s_lshl_b32 s21, s4, 8
	s_addk_i32 s5, 0x2000
	s_add_u32 s10, s10, 0x10800000
	s_addc_u32 s11, s11, 0
	v_sub_f32_e32 v16, v16, v32
	v_sub_f32_e32 v17, v17, v32
	v_sub_f32_e32 v18, v18, v32
	v_sub_f32_e32 v19, v19, v32
	v_sub_f32_e32 v20, v20, v32
	v_sub_f32_e32 v21, v21, v32
	v_sub_f32_e32 v22, v22, v32
	v_sub_f32_e32 v23, v23, v32
	v_sub_f32_e32 v24, v24, v32
	v_sub_f32_e32 v25, v25, v32
	v_sub_f32_e32 v26, v26, v32
	v_sub_f32_e32 v27, v27, v32
	v_sub_f32_e32 v28, v28, v32
	v_sub_f32_e32 v29, v29, v32
	v_sub_f32_e32 v30, v30, v32
	v_sub_f32_e32 v31, v31, v32
	v_add_lshl_u32 v2, v82, v81, 1
	s_add_u32 s4, s21, s0
	v_exp_f32_e32 v161, v16
	v_exp_f32_e32 v196, v17
	v_exp_f32_e32 v158, v18
	v_exp_f32_e32 v168, v19
	v_exp_f32_e32 v159, v20
	v_exp_f32_e32 v169, v21
	v_exp_f32_e32 v160, v22
	v_exp_f32_e32 v195, v23
	v_exp_f32_e32 v150, v24
	v_exp_f32_e32 v154, v25
	v_exp_f32_e32 v151, v26
	v_exp_f32_e32 v155, v27
	v_exp_f32_e32 v152, v28
	v_exp_f32_e32 v156, v29
	v_exp_f32_e32 v153, v30
	v_exp_f32_e32 v157, v31
	v_sub_f32_e32 v67, v3, v32
	v_add_u32_e32 v190, s5, v0
	v_or_b32_e32 v112, 0x4000, v2
	s_addc_u32 s5, 0, s1
	v_and_b32_e32 v3, 7, v80
	v_lshl_add_u64 v[162:163], s[10:11], 0, v[112:113]
	v_lshl_add_u64 v[0:1], s[4:5], 0, v[44:45]
	v_lshlrev_b32_e32 v112, 4, v3
	v_xor_b32_e32 v48, 0x80000000, v32
	v_lshl_add_u64 v[164:165], v[0:1], 0, v[112:113]
	v_add_u32_e32 v112, 0x3000, v2
	v_mov_b32_e32 v0, 0
	v_mov_b32_e32 v49, v48
	v_mov_b32_e32 v50, v48
	v_mov_b32_e32 v51, v48
	v_mov_b32_e32 v52, v48
	v_mov_b32_e32 v53, v48
	v_mov_b32_e32 v54, v48
	v_mov_b32_e32 v55, v48
	v_mov_b32_e32 v56, v48
	v_mov_b32_e32 v57, v48
	v_mov_b32_e32 v58, v48
	v_mov_b32_e32 v59, v48
	v_mov_b32_e32 v60, v48
	v_mov_b32_e32 v61, v48
	v_mov_b32_e32 v62, v48
	v_mov_b32_e32 v63, v48
; #define SBAR() __builtin_amdgcn_sched_barrier(0)
; #define SLOAD(i, k0) do { st_[i].vs = *reinterpret_cast<const bf16x8*>(&Vh[(size_t)((k0) + sr) * LDK + sc]); \
;     st_[i].ks = *reinterpret_cast<const bf16x8*>(&Kh[(size_t)((k0) + sr) * LDK + sc]); \
;     if (DQ == 96) st_[i].kr = *reinterpret_cast<const bf16x8*>(&Kr[(size_t)((k0) + sr2) * 32 + sc2]); } while (0)
; #define SWRITE(b, i) do { *(bf16x8*)(V_lds + (b) * SHM_V + vst0) = st_[i].vs; *(bf16x8*)(K_lds + (b) * SHM_K + kst0) = st_[i].ks; \
;     if (DQ == 96) { if (tid < 256) *(bf16x8*)(K_lds + (b) * SHM_K + kst2) = st_[i].kr; } } while (0)
; #define SWAIT() do { if (DQ == 96) asm volatile("s_waitcnt vmcnt(3)" ::: "memory"); else asm volatile("s_waitcnt vmcnt(2)" ::: "memory"); } while (0)
; #define SLOAD(i, k0) do { st_[i].vs = *reinterpret_cast<const bf16x8*>(&Vh[(size_t)((k0) + sr) * LDK + sc]); \
;     st_[i].ks = *reinterpret_cast<const bf16x8*>(&Kh[(size_t)((k0) + sr) * LDK + sc]); \
;     if (DQ == 96) st_[i].kr = *reinterpret_cast<const bf16x8*>(&Kr[(size_t)((k0) + sr2) * 32 + sc2]); } while (0)
; #define SWRITE(b, i) do { *(bf16x8*)(V_lds + (b) * SHM_V + vst0) = st_[i].vs; *(bf16x8*)(K_lds + (b) * SHM_K + kst0) = st_[i].ks; \
;     if (DQ == 96) { if (tid < 256) *(bf16x8*)(K_lds + (b) * SHM_K + kst2) = st_[i].kr; } } while (0)
; #define SWAIT() do { if (DQ == 96) asm volatile("s_waitcnt vmcnt(3)" ::: "memory"); else asm volatile("s_waitcnt vmcnt(2)" ::: "memory"); } while (0)
; template <int DQ, bool WIN, int LDQ, int LDK> ...
;     ...
;       for (int r = 0; r < 16; ++r) { minit[r] = -m_ref; pA0[r] -= m_ref; pA1[r] -= m_ref; } }
;     exp16(pA0);
;     if (2 < NT) SLOAD(SE, KBASE(2));
;     SWAIT(); SWRITE(1, SO); __syncthreads();
; #pragma unroll 1
;     for (int j = 1; j + 1 < NT; j += 2) {
;         SBAR(); qkt<DQ>(pB0, pB1, K_lds + SHM_K, qr, minit, r32, hi);
;         finish(pA0, pA1); SBAR();
;         SLOAD(SO, KBASE(j + 2)); SBAR();
;         pv(vb0);
;         __syncthreads(); SWAIT(); SWRITE(0, SE);
;         lsum_upd();
;         if (WIN) win_mask(pB0, pB1, qrow - KBASE(j), hi);
;         exp16(pB0);
;         __syncthreads();
;         SBAR(); qkt<DQ>(pA0, pA1, K_lds, qr, minit, r32, hi);
	v_sub_f32_e32 v79, v15, v32
	v_sub_f32_e32 v78, v14, v32
	v_sub_f32_e32 v77, v13, v32
	v_sub_f32_e32 v76, v12, v32
	v_sub_f32_e32 v75, v11, v32
	v_sub_f32_e32 v74, v10, v32
	v_sub_f32_e32 v73, v9, v32
	v_sub_f32_e32 v72, v8, v32
	v_sub_f32_e32 v71, v7, v32
	v_sub_f32_e32 v70, v6, v32
	v_sub_f32_e32 v69, v5, v32
	v_sub_f32_e32 v68, v4, v32
	s_mov_b32 s17, -1
	v_lshl_add_u64 v[166:167], s[10:11], 0, v[112:113]
	v_add_u32_e32 v112, 0, v36
	v_mov_b32_e32 v1, v0
	v_mov_b32_e32 v2, v0
	v_mov_b32_e32 v3, v0
	v_mov_b32_e32 v4, v0
	v_mov_b32_e32 v5, v0
	v_mov_b32_e32 v6, v0
	v_mov_b32_e32 v7, v0
	v_mov_b32_e32 v8, v0
	v_mov_b32_e32 v9, v0
	v_mov_b32_e32 v10, v0
	v_mov_b32_e32 v11, v0
	v_mov_b32_e32 v12, v0
	v_mov_b32_e32 v13, v0
	v_mov_b32_e32 v14, v0
	v_mov_b32_e32 v15, v0
	v_mov_b32_e32 v16, v0
	v_mov_b32_e32 v17, v0
	v_mov_b32_e32 v18, v0
	v_mov_b32_e32 v19, v0
	v_mov_b32_e32 v20, v0
	v_mov_b32_e32 v21, v0
	v_mov_b32_e32 v22, v0
	v_mov_b32_e32 v23, v0
	v_mov_b32_e32 v24, v0
	v_mov_b32_e32 v25, v0
	v_mov_b32_e32 v26, v0
	v_mov_b32_e32 v27, v0
	v_mov_b32_e32 v28, v0
	v_mov_b32_e32 v29, v0
	v_mov_b32_e32 v30, v0
	v_mov_b32_e32 v31, v0
	v_mov_b32_e32 v32, v0
	v_mov_b32_e32 v33, v0
	v_mov_b32_e32 v34, v0
	v_mov_b32_e32 v35, v0
	v_lshrrev_b32_e32 v36, 4, v189
	v_xor_b32_e32 v36, v36, v189
	v_not_b32_e32 v36, v36
	v_bfe_i32 v36, v36, 0, 1
	v_and_b32_e32 v36, 0x3f803f80, v36
	v_mov_b32_e32 v37, v36
	v_mov_b32_e32 v38, v36
	v_mov_b32_e32 v39, v36
	v_mov_b32_e32 v40, v0
	v_mov_b32_e32 v41, v0
	v_mov_b32_e32 v42, v0
	v_mov_b32_e32 v43, v0
	v_mov_b32_e32 v44, v0
	v_mov_b32_e32 v45, v0
	v_mov_b32_e32 v46, v0
	v_mov_b32_e32 v47, v0
	v_xor_b32_e32 v192, 0xc000, v192
	s_mov_b64 s[34:35], 0x2000
	s_mov_b64 s[18:19], 0x80000
	s_waitcnt lgkmcnt(0)
	s_barrier
	s_branch .LBB0_1094
.LBB0_1093:
	v_xor_b32_e32 v192, 0xc000, v192
	v_xor_b32_e32 v194, 0xc000, v194
	v_xor_b32_e32 v190, 0xc000, v190
	v_exp_f32_e32 v161, v96
	v_exp_f32_e32 v196, v97
	v_mfma_f32_16x16x32_bf16 v[32:35], v[80:83], v[36:39], v[32:35]
	v_exp_f32_e32 v158, v98
	v_exp_f32_e32 v168, v99
	v_exp_f32_e32 v159, v100
	v_exp_f32_e32 v169, v101
	v_exp_f32_e32 v160, v102
	v_exp_f32_e32 v195, v103
	v_exp_f32_e32 v154, v105
	v_mfma_f32_16x16x32_bf16 v[32:35], v[84:87], v[36:39], v[32:35]
	v_exp_f32_e32 v155, v107
	v_exp_f32_e32 v156, v109
	v_exp_f32_e32 v157, v111
	v_lshl_add_u64 v[162:163], v[162:163], 0, s[34:35]
	v_lshl_add_u64 v[164:165], v[164:165], 0, s[18:19]
	v_mfma_f32_16x16x32_bf16 v[32:35], v[88:91], v[36:39], v[32:35]
	v_lshl_add_u64 v[166:167], v[166:167], 0, s[34:35]
	s_waitcnt lgkmcnt(0)
	s_barrier
	v_mfma_f32_16x16x32_bf16 v[32:35], v[92:95], v[36:39], v[32:35]
	v_exp_f32_e32 v150, v104
	v_exp_f32_e32 v151, v106
	v_exp_f32_e32 v152, v108
	v_exp_f32_e32 v153, v110
	s_cmpk_gt_u32 s17, 0x7c
	s_cbranch_scc1 .LBB0_1100
.LBB0_1094:
	ds_read_b64_tr_b16 v[40:41], v194 offset:0
	ds_read_b64_tr_b16 v[42:43], v194 offset:0x400
	ds_read_b64_tr_b16 v[44:45], v194 offset:0x800
	ds_read_b64_tr_b16 v[46:47], v194 offset:0xc00
	ds_read_b128 v[198:201], v191 offset:36352
	ds_read_b128 v[80:83], v191 offset:29696
	ds_read_b128 v[202:205], v191 offset:29728
	v_exp_f32_e32 v72, v72
	v_exp_f32_e32 v73, v73
	v_exp_f32_e32 v74, v74
	s_waitcnt lgkmcnt(1)
	v_mfma_f32_32x32x16_bf16 v[96:111], v[80:83], v[134:137], v[48:63]
	v_exp_f32_e32 v75, v75
	v_exp_f32_e32 v197, v64
	v_exp_f32_e32 v206, v77
	v_exp_f32_e32 v207, v78
	v_exp_f32_e32 v208, v79
	v_mfma_f32_32x32x16_bf16 v[80:95], v[198:201], v[134:137], v[48:63]
	ds_read_b128 v[198:201], v191 offset:36384
	s_waitcnt lgkmcnt(1)
	v_mfma_f32_32x32x16_bf16 v[96:111], v[202:205], v[130:133], v[96:111]
	s_waitcnt lgkmcnt(0)
	v_mfma_f32_32x32x16_bf16 v[80:95], v[198:201], v[130:133], v[80:95]
	ds_read_b128 v[198:201], v191 offset:29760
	ds_read_b128 v[202:205], v191 offset:36416
	s_waitcnt lgkmcnt(1)
	v_mfma_f32_32x32x16_bf16 v[96:111], v[198:201], v[126:129], v[96:111]
	s_waitcnt lgkmcnt(0)
	v_mfma_f32_32x32x16_bf16 v[80:95], v[202:205], v[126:129], v[80:95]
	ds_read_b128 v[198:201], v191 offset:29792
	ds_read_b128 v[202:205], v191 offset:36448
	s_waitcnt lgkmcnt(1)
	v_mfma_f32_32x32x16_bf16 v[96:111], v[198:201], v[122:125], v[96:111]
	s_waitcnt lgkmcnt(0)
	v_mfma_f32_32x32x16_bf16 v[80:95], v[202:205], v[122:125], v[80:95]
	ds_read_b128 v[198:201], v191 offset:29824
	ds_read_b128 v[202:205], v191 offset:36480
	s_waitcnt lgkmcnt(1)
	v_mfma_f32_32x32x16_bf16 v[96:111], v[198:201], v[118:121], v[96:111]
	s_waitcnt lgkmcnt(0)
	v_mfma_f32_32x32x16_bf16 v[80:95], v[202:205], v[118:121], v[80:95]
	ds_read_b128 v[198:201], v191 offset:29856
	ds_read_b128 v[202:205], v191 offset:36512
	s_waitcnt lgkmcnt(1)
	v_mfma_f32_32x32x16_bf16 v[96:111], v[198:201], v[114:117], v[96:111]
	v_exp_f32_e32 v198, v65
	v_exp_f32_e32 v199, v66
	v_exp_f32_e32 v200, v67
	v_exp_f32_e32 v201, v68
	v_cvt_pk_bf16_f32 v68, v161, v196
	s_waitcnt lgkmcnt(0)
; #define SWRITE(b, i) do { *(bf16x8*)(V_lds + (b) * SHM_V + vst0) = st_[i].vs; *(bf16x8*)(K_lds + (b) * SHM_K + kst0) = st_[i].ks; \
;     if (DQ == 96) { if (tid < 256) *(bf16x8*)(K_lds + (b) * SHM_K + kst2) = st_[i].kr; } } while (0)
; #define SWAIT() do { if (DQ == 96) asm volatile("s_waitcnt vmcnt(3)" ::: "memory"); else asm volatile("s_waitcnt vmcnt(2)" ::: "memory"); } while (0)
; #define SWRITE(b, i) do { *(bf16x8*)(V_lds + (b) * SHM_V + vst0) = st_[i].vs; *(bf16x8*)(K_lds + (b) * SHM_K + kst0) = st_[i].ks; \
;     if (DQ == 96) { if (tid < 256) *(bf16x8*)(K_lds + (b) * SHM_K + kst2) = st_[i].kr; } } while (0)
; #define SWAIT() do { if (DQ == 96) asm volatile("s_waitcnt vmcnt(3)" ::: "memory"); else asm volatile("s_waitcnt vmcnt(2)" ::: "memory"); } while (0)
; template <int DQ, bool WIN, int LDQ, int LDK> ...
;     ...
;         pv(vb0);
;         __syncthreads(); SWAIT(); SWRITE(0, SE);
;         lsum_upd();
	v_mfma_f32_32x32x16_bf16 v[80:95], v[202:205], v[114:117], v[80:95]
	v_exp_f32_e32 v202, v69
	v_exp_f32_e32 v203, v70
	v_exp_f32_e32 v204, v71
	v_exp_f32_e32 v205, v76
	v_cvt_pk_bf16_f32 v69, v158, v168
	v_cvt_pk_bf16_f32 v70, v159, v169
	v_cvt_pk_bf16_f32 v71, v160, v195
	v_cvt_pk_bf16_f32 v64, v150, v154
	v_cvt_pk_bf16_f32 v65, v151, v155
	v_cvt_pk_bf16_f32 v66, v152, v156
	v_cvt_pk_bf16_f32 v67, v153, v157
	v_cvt_pk_bf16_f32 v76, v197, v198
	v_cvt_pk_bf16_f32 v77, v199, v200
	v_cvt_pk_bf16_f32 v78, v201, v202
	v_cvt_pk_bf16_f32 v79, v203, v204
	v_cvt_pk_bf16_f32 v72, v72, v73
	v_cvt_pk_bf16_f32 v73, v74, v75
	v_cvt_pk_bf16_f32 v74, v205, v206
	v_cvt_pk_bf16_f32 v75, v207, v208
	v_lshl_add_u64 v[168:169], s[26:27], 0, v[164:165]
	s_mov_b32 s4, 0x218c0000
	v_add_co_u32_e32 v150, vcc, s4, v168
	s_nop 1
	v_addc_co_u32_e32 v151, vcc, 0, v169, vcc
	global_load_dwordx4 v[154:157], v[150:151], off offset:128
	global_load_dwordx4 v[158:161], v[150:151], off
	v_lshl_add_u64 v[150:151], s[26:27], 0, v[166:167]
	global_load_dwordx4 v[150:153], v[150:151], off
	ds_read_b64_tr_b16 v[204:205], v194 offset:0x1000
	ds_read_b64_tr_b16 v[206:207], v194 offset:0x1400
	ds_read_b64_tr_b16 v[208:209], v194 offset:0x1800
	ds_read_b64_tr_b16 v[210:211], v194 offset:0x1c00
	ds_read_b64_tr_b16 v[196:197], v194 offset:0x200
	ds_read_b64_tr_b16 v[198:199], v194 offset:0x600
	ds_read_b64_tr_b16 v[200:201], v194 offset:0xa00
	ds_read_b64_tr_b16 v[202:203], v194 offset:0xe00
	s_nop 0
	v_mfma_f32_32x32x16_bf16 v[0:15], v[68:71], v[40:43], v[0:15]
	v_mfma_f32_32x32x16_bf16 v[0:15], v[64:67], v[44:47], v[0:15]
	s_waitcnt lgkmcnt(6)
	v_mfma_f32_32x32x16_bf16 v[0:15], v[76:79], v[204:207], v[0:15]
	ds_read_b64_tr_b16 v[204:205], v194 offset:0x1200
	ds_read_b64_tr_b16 v[206:207], v194 offset:0x1600
	s_waitcnt lgkmcnt(6)
	v_mfma_f32_32x32x16_bf16 v[0:15], v[72:75], v[208:211], v[0:15]
	ds_read_b64_tr_b16 v[208:209], v194 offset:0x1a00
	ds_read_b64_tr_b16 v[210:211], v194 offset:0x1e00
	s_waitcnt lgkmcnt(0)
	v_mfma_f32_32x32x16_bf16 v[16:31], v[68:71], v[196:199], v[16:31]
	s_waitcnt vmcnt(3)
	s_waitcnt vmcnt(5)
	ds_write_b128 v192, v[138:141]
	s_waitcnt vmcnt(4)
	ds_write_b128 v193, v[142:145] offset:16384
	v_mfma_f32_32x32x16_bf16 v[16:31], v[64:67], v[200:203], v[16:31]
	v_mfma_f32_32x32x16_bf16 v[16:31], v[76:79], v[204:207], v[16:31]
	v_mfma_f32_32x32x16_bf16 v[16:31], v[72:75], v[208:211], v[16:31]
	ds_write_b128 v112, v[146:149] offset:16512
; #define SBAR() __builtin_amdgcn_sched_barrier(0)
; #define SLOAD(i, k0) do { st_[i].vs = *reinterpret_cast<const bf16x8*>(&Vh[(size_t)((k0) + sr) * LDK + sc]); \
;     st_[i].ks = *reinterpret_cast<const bf16x8*>(&Kh[(size_t)((k0) + sr) * LDK + sc]); \
;     if (DQ == 96) st_[i].kr = *reinterpret_cast<const bf16x8*>(&Kr[(size_t)((k0) + sr2) * 32 + sc2]); } while (0)
; #define SWRITE(b, i) do { *(bf16x8*)(V_lds + (b) * SHM_V + vst0) = st_[i].vs; *(bf16x8*)(K_lds + (b) * SHM_K + kst0) = st_[i].ks; \
;     if (DQ == 96) { if (tid < 256) *(bf16x8*)(K_lds + (b) * SHM_K + kst2) = st_[i].kr; } } while (0)
; #define SWAIT() do { if (DQ == 96) asm volatile("s_waitcnt vmcnt(3)" ::: "memory"); else asm volatile("s_waitcnt vmcnt(2)" ::: "memory"); } while (0)
; #define SLOAD(i, k0) do { st_[i].vs = *reinterpret_cast<const bf16x8*>(&Vh[(size_t)((k0) + sr) * LDK + sc]); \
;     st_[i].ks = *reinterpret_cast<const bf16x8*>(&Kh[(size_t)((k0) + sr) * LDK + sc]); \
;     if (DQ == 96) st_[i].kr = *reinterpret_cast<const bf16x8*>(&Kr[(size_t)((k0) + sr2) * 32 + sc2]); } while (0)
; #define SWRITE(b, i) do { *(bf16x8*)(V_lds + (b) * SHM_V + vst0) = st_[i].vs; *(bf16x8*)(K_lds + (b) * SHM_K + kst0) = st_[i].ks; \
;     if (DQ == 96) { if (tid < 256) *(bf16x8*)(K_lds + (b) * SHM_K + kst2) = st_[i].kr; } } while (0)
; #define SWAIT() do { if (DQ == 96) asm volatile("s_waitcnt vmcnt(3)" ::: "memory"); else asm volatile("s_waitcnt vmcnt(2)" ::: "memory"); } while (0)
; template <int DQ, bool WIN, int LDQ, int LDK> ...
;     ...
;         lsum_upd();
;         if (WIN) win_mask(pB0, pB1, qrow - KBASE(j), hi);
;         exp16(pB0);
;         __syncthreads();
;         SBAR(); qkt<DQ>(pA0, pA1, K_lds, qr, minit, r32, hi);
;         finish(pB0, pB1); SBAR();
;         if (j + 3 < NT) SLOAD(SE, KBASE(j + 3)); SBAR();
;         pv(vb0 + SHM_V);
;         __syncthreads(); SWAIT(); SWRITE(1, SO);
;         lsum_upd();
;         if (WIN) win_mask(pA0, pA1, qrow - KBASE(j + 1), hi);
;         exp16(pA0);
;         __syncthreads();
;     }
.LBB0_1096:
	s_add_i32 s17, s17, 2
	v_exp_f32_e32 v195, v96
	v_mfma_f32_16x16x32_bf16 v[32:35], v[68:71], v[36:39], v[32:35]
	v_exp_f32_e32 v204, v97
	v_exp_f32_e32 v205, v98
	v_exp_f32_e32 v206, v99
	v_exp_f32_e32 v207, v100
	v_exp_f32_e32 v208, v101
	v_exp_f32_e32 v209, v102
	v_exp_f32_e32 v210, v103
	v_mfma_f32_16x16x32_bf16 v[32:35], v[64:67], v[36:39], v[32:35]
	v_exp_f32_e32 v211, v104
	v_exp_f32_e32 v212, v105
	v_exp_f32_e32 v213, v106
	v_exp_f32_e32 v214, v107
	v_exp_f32_e32 v215, v108
	v_exp_f32_e32 v216, v109
	v_exp_f32_e32 v217, v110
	v_mfma_f32_16x16x32_bf16 v[32:35], v[76:79], v[36:39], v[32:35]
	v_exp_f32_e32 v218, v111
	s_waitcnt lgkmcnt(0)
	s_barrier
	v_mfma_f32_16x16x32_bf16 v[32:35], v[72:75], v[36:39], v[32:35]
	ds_read_b64_tr_b16 v[40:41], v190 offset:0
	ds_read_b64_tr_b16 v[42:43], v190 offset:0x400
	ds_read_b64_tr_b16 v[44:45], v190 offset:0x800
	ds_read_b64_tr_b16 v[46:47], v190 offset:0xc00
	ds_read_b128 v[196:199], v191 offset:23040
	ds_read_b128 v[64:67], v191 offset:16384
	ds_read_b128 v[200:203], v191 offset:16416
	v_exp_f32_e32 v95, v95
	v_exp_f32_e32 v219, v88
	v_exp_f32_e32 v220, v89
	s_waitcnt lgkmcnt(1)
	v_mfma_f32_32x32x16_bf16 v[96:111], v[64:67], v[134:137], v[48:63]
	v_exp_f32_e32 v221, v90
	v_exp_f32_e32 v222, v91
	v_exp_f32_e32 v223, v92
	v_exp_f32_e32 v224, v93
	v_exp_f32_e32 v225, v94
	v_mfma_f32_32x32x16_bf16 v[64:79], v[196:199], v[134:137], v[48:63]
	ds_read_b128 v[196:199], v191 offset:23072
	s_waitcnt lgkmcnt(1)
	v_mfma_f32_32x32x16_bf16 v[96:111], v[200:203], v[130:133], v[96:111]
	s_waitcnt lgkmcnt(0)
	v_mfma_f32_32x32x16_bf16 v[64:79], v[196:199], v[130:133], v[64:79]
	ds_read_b128 v[196:199], v191 offset:16448
	ds_read_b128 v[200:203], v191 offset:23104
	s_waitcnt lgkmcnt(1)
	v_mfma_f32_32x32x16_bf16 v[96:111], v[196:199], v[126:129], v[96:111]
	s_waitcnt lgkmcnt(0)
	v_mfma_f32_32x32x16_bf16 v[64:79], v[200:203], v[126:129], v[64:79]
	ds_read_b128 v[196:199], v191 offset:16480
	ds_read_b128 v[200:203], v191 offset:23136
	s_waitcnt lgkmcnt(1)
	v_mfma_f32_32x32x16_bf16 v[96:111], v[196:199], v[122:125], v[96:111]
	s_waitcnt lgkmcnt(0)
	v_mfma_f32_32x32x16_bf16 v[64:79], v[200:203], v[122:125], v[64:79]
	ds_read_b128 v[196:199], v191 offset:16512
	ds_read_b128 v[200:203], v191 offset:23168
	s_waitcnt lgkmcnt(1)
	v_mfma_f32_32x32x16_bf16 v[96:111], v[196:199], v[118:121], v[96:111]
	s_waitcnt lgkmcnt(0)
	v_mfma_f32_32x32x16_bf16 v[64:79], v[200:203], v[118:121], v[64:79]
	ds_read_b128 v[196:199], v191 offset:16544
	ds_read_b128 v[200:203], v191 offset:23200
	s_waitcnt lgkmcnt(1)
	v_mfma_f32_32x32x16_bf16 v[96:111], v[196:199], v[114:117], v[96:111]
	v_exp_f32_e32 v196, v80
	v_exp_f32_e32 v197, v81
	v_exp_f32_e32 v198, v82
	v_exp_f32_e32 v199, v83
	v_cvt_pk_bf16_f32 v80, v195, v204
	v_cvt_pk_bf16_f32 v81, v205, v206
	v_cvt_pk_bf16_f32 v82, v207, v208
	s_waitcnt lgkmcnt(0)
	v_mfma_f32_32x32x16_bf16 v[64:79], v[200:203], v[114:117], v[64:79]
	v_exp_f32_e32 v200, v84
	v_exp_f32_e32 v201, v85
	v_exp_f32_e32 v202, v86
	v_exp_f32_e32 v203, v87
	v_cvt_pk_bf16_f32 v83, v209, v210
	v_cvt_pk_bf16_f32 v84, v211, v212
	v_cvt_pk_bf16_f32 v85, v213, v214
	v_cvt_pk_bf16_f32 v86, v215, v216
	v_cvt_pk_bf16_f32 v87, v217, v218
	v_cvt_pk_bf16_f32 v88, v196, v197
	v_cvt_pk_bf16_f32 v89, v198, v199
	v_cvt_pk_bf16_f32 v90, v200, v201
	v_cvt_pk_bf16_f32 v91, v202, v203
	v_cvt_pk_bf16_f32 v92, v219, v220
	v_cvt_pk_bf16_f32 v93, v221, v222
	v_cvt_pk_bf16_f32 v94, v223, v224
	v_cvt_pk_bf16_f32 v95, v225, v95
	v_add_co_u32_e32 v142, vcc, 0x21900000, v168
	s_waitcnt vmcnt(3)
	v_lshl_add_u64 v[146:147], s[26:27], 0, v[162:163]
	v_addc_co_u32_e32 v143, vcc, 0, v169, vcc
	global_load_dwordx4 v[138:141], v[142:143], off offset:128
	s_nop 0
	global_load_dwordx4 v[142:145], v[142:143], off
	s_nop 0
	global_load_dwordx4 v[146:149], v[146:147], off
.LBB0_1098:
	ds_read_b64_tr_b16 v[204:205], v190 offset:0x1000
	ds_read_b64_tr_b16 v[206:207], v190 offset:0x1400
	ds_read_b64_tr_b16 v[208:209], v190 offset:0x1800
	ds_read_b64_tr_b16 v[210:211], v190 offset:0x1c00
	ds_read_b64_tr_b16 v[196:197], v190 offset:0x200
	ds_read_b64_tr_b16 v[198:199], v190 offset:0x600
	ds_read_b64_tr_b16 v[200:201], v190 offset:0xa00
	ds_read_b64_tr_b16 v[202:203], v190 offset:0xe00
	s_nop 0
	v_mfma_f32_32x32x16_bf16 v[0:15], v[80:83], v[40:43], v[0:15]
	v_mfma_f32_32x32x16_bf16 v[0:15], v[84:87], v[44:47], v[0:15]
	s_waitcnt lgkmcnt(6)
	v_mfma_f32_32x32x16_bf16 v[0:15], v[88:91], v[204:207], v[0:15]
	ds_read_b64_tr_b16 v[204:205], v190 offset:0x1200
	ds_read_b64_tr_b16 v[206:207], v190 offset:0x1600
	s_waitcnt lgkmcnt(6)
	v_mfma_f32_32x32x16_bf16 v[0:15], v[92:95], v[208:211], v[0:15]
	ds_read_b64_tr_b16 v[208:209], v190 offset:0x1a00
	ds_read_b64_tr_b16 v[210:211], v190 offset:0x1e00
	s_waitcnt lgkmcnt(0)
	v_mfma_f32_32x32x16_bf16 v[16:31], v[80:83], v[196:199], v[16:31]
	s_waitcnt vmcnt(3)
	ds_write_b128 v192, v[154:157] offset:8192
	ds_write_b128 v193, v[158:161] offset:29696
	v_mfma_f32_32x32x16_bf16 v[16:31], v[84:87], v[200:203], v[16:31]
	v_mfma_f32_32x32x16_bf16 v[16:31], v[88:91], v[204:207], v[16:31]
	v_mfma_f32_32x32x16_bf16 v[16:31], v[92:95], v[208:211], v[16:31]
	ds_write_b128 v112, v[150:153] offset:29824
	s_branch .LBB0_1093
